# attention item->(chunk,headpair) remap so an XCD's blocks cover consecutive chunks of one head pair (L2 reuse of K/V)
# speedup vs baseline: 1.0097x; 1.0097x over previous
; __device__ __forceinline__ unsigned cvt_pk_bf16(float lo, float hi) { unsigned r; asm("v_cvt_pk_bf16_f32 %0, %1, %2" : "=v"(r) : "v"(lo), "v"(hi)); return r; }
; __device__ __forceinline__ float lo_bf(unsigned u) { return __uint_as_float(u << 16); }
; __device__ __forceinline__ float hi_bf(unsigned u) { return __uint_as_float(u & 0xffff0000u); }
; __device__ __forceinline__ void attn_phase(const Params& p, int l, bf16_t* PROJ, LAS unsigned char* L) {
;     ...
;         const int n = item >> 2, hp = item & 3, h = hp * 2 + hh;
;         __syncthreads();
;         for (int i = tid; i < 640; i += 512) { const int h2 = i / 320, k = i - h2 * 320; relb[i] = p.rel_bias[(size_t)(l * 8 + hp * 2 + h2) * 513 + 193 + k] * 1.4426950408889634f; }
;         bf16x8 aq[4];
;         {
;             const bf16_t* qp = PROJ + (size_t)(n * 64 + rt * 16 + fr) * INW + AQ + h * 128 + fq * 8;
;             u32x4 raw[4]; float ss = 0.f;
; #pragma unroll
;             for (int ks = 0; ks < 4; ++ks) { raw[ks] = *(const u32x4*)(qp + ks * 32);
; #pragma unroll
;                 for (int e = 0; e < 4; ++e) { const float a = lo_bf(raw[ks][e]), b = hi_bf(raw[ks][e]); ss += a * a + b * b; } }
;             ss += __shfl_xor(ss, 16); ss += __shfl_xor(ss, 32);
;             const float rs = rsqrtf(ss * (1.0f / 128.0f) + EPS) * (0.08838834764831845f * 1.4426950408889634f);
; #pragma unroll
;             for (int ks = 0; ks < 4; ++ks) { const float* gp = gq + ks * 32 + fq * 8; const float* gkp = gk + ks * 32 + fq * 8; u32x4 w;
; #pragma unroll
;                 for (int e = 0; e < 4; ++e) w[e] = cvt_pk_bf16(lo_bf(raw[ks][e]) * rs * gp[2 * e] * gkp[2 * e], hi_bf(raw[ks][e]) * rs * gp[2 * e + 1] * gkp[2 * e + 1]);
;                 aq[ks] = __builtin_bit_cast(bf16x8, w); }
.LBB0_346:
	s_or_b64 exec, exec, s[20:21]
	s_bfe_u32 s20, s43, 0x50003
	s_bfe_u32 s21, s43, 0x10002
	s_lshl_b32 s21, s21, 5
	s_or_b32 s20, s20, s21
	s_bfe_u32 s21, s43, 0x20008
	s_lshl_b32 s21, s21, 6
	s_or_b32 s20, s20, s21
	v_lshl_or_b32 v216, s20, 6, v151
	v_or_b32_e32 v2, v216, v103
	v_mov_b64_e32 v[0:1], s[14:15]
	v_add_lshl_u32 v114, s36, v150, 7
	v_mad_i64_i32 v[0:1], s[22:23], v2, s62, v[0:1]
	v_ashrrev_i32_e32 v115, 31, v114
	v_lshl_add_u64 v[0:1], v[114:115], 1, v[0:1]
	v_mov_b32_e32 v113, v137
	v_lshl_add_u64 v[0:1], v[0:1], 0, v[112:113]
	global_load_dwordx4 v[2:5], v[0:1], off
	global_load_dwordx4 v[30:33], v[0:1], off offset:192
	global_load_dwordx4 v[34:37], v[100:101], off
	s_sub_i32 s3, 8, s20
	s_cmp_lt_i32 s20, 8
	s_cselect_b32 s3, s3, 0
	v_mov_b32_e32 v119, 0
	s_cmp_lt_i32 s3, 9
	v_mov_b32_e32 v118, v119
	v_mov_b32_e32 v117, v119
	v_mov_b32_e32 v116, v119
	v_mov_b32_e32 v43, v119
	v_mov_b32_e32 v47, v119
	v_mov_b32_e32 v46, v119
	v_mov_b32_e32 v45, v119
	v_mov_b32_e32 v44, v119
	s_waitcnt vmcnt(2)
	v_and_b32_e32 v38, 0xffff0000, v2
	v_and_b32_e32 v40, 0xffff0000, v3
	v_lshlrev_b32_e32 v29, 16, v2
	v_mul_f32_e32 v2, v38, v38
	v_lshlrev_b32_e32 v39, 16, v3
	v_mul_f32_e32 v3, v40, v40
	v_fmac_f32_e32 v2, v29, v29
	v_fmac_f32_e32 v3, v39, v39
	v_add_f32_e32 v3, v2, v3
	v_and_b32_e32 v2, 0xffff0000, v4
	v_lshlrev_b32_e32 v41, 16, v4
	v_mul_f32_e32 v4, v2, v2
	v_fmac_f32_e32 v4, v41, v41
	v_add_f32_e32 v6, v4, v3
	v_and_b32_e32 v3, 0xffff0000, v5
	v_lshlrev_b32_e32 v4, 16, v5
	v_mul_f32_e32 v5, v3, v3
	v_fmac_f32_e32 v5, v4, v4
	v_add_f32_e32 v5, v5, v6
	global_load_dwordx4 v[6:9], v[0:1], off offset:64
	s_waitcnt vmcnt(2)
	v_lshlrev_b32_e32 v17, 16, v31
	v_lshlrev_b32_e32 v25, 16, v33
	v_lshlrev_b32_e32 v24, 16, v32
	v_and_b32_e32 v23, 0xffff0000, v33
	s_waitcnt vmcnt(0)
	v_and_b32_e32 v27, 0xffff0000, v6
	v_lshlrev_b32_e32 v42, 16, v6
	v_mul_f32_e32 v6, v27, v27
	v_fmac_f32_e32 v6, v42, v42
	v_add_f32_e32 v6, v6, v5
	v_and_b32_e32 v5, 0xffff0000, v7
	v_lshlrev_b32_e32 v28, 16, v7
	v_mul_f32_e32 v7, v5, v5
	v_fmac_f32_e32 v7, v28, v28
	v_add_f32_e32 v7, v7, v6
	v_and_b32_e32 v6, 0xffff0000, v8
	v_lshlrev_b32_e32 v21, 16, v8
	v_mul_f32_e32 v8, v6, v6
	v_fmac_f32_e32 v8, v21, v21
	v_add_f32_e32 v8, v8, v7
	v_and_b32_e32 v7, 0xffff0000, v9
	v_lshlrev_b32_e32 v20, 16, v9
	v_mul_f32_e32 v9, v7, v7
	v_fmac_f32_e32 v9, v20, v20
	v_add_f32_e32 v14, v9, v8
	global_load_dwordx4 v[8:11], v[0:1], off offset:128
	s_waitcnt vmcnt(0)
	v_lshlrev_b32_e32 v19, 16, v9
	v_lshlrev_b32_e32 v18, 16, v8
	v_and_b32_e32 v9, 0xffff0000, v9
	v_and_b32_e32 v8, 0xffff0000, v8
	v_pk_mul_f32 v[12:13], v[8:9], v[8:9]
	s_nop 0
	v_pk_fma_f32 v[12:13], v[18:19], v[18:19], v[12:13]
	s_nop 0
	v_add_f32_e32 v12, v12, v14
	v_add_f32_e32 v16, v13, v12
	v_lshlrev_b32_e32 v13, 16, v11
	v_lshlrev_b32_e32 v12, 16, v10
	v_and_b32_e32 v11, 0xffff0000, v11
	v_and_b32_e32 v10, 0xffff0000, v10
	v_pk_mul_f32 v[14:15], v[10:11], v[10:11]
	s_nop 0
	v_pk_fma_f32 v[14:15], v[12:13], v[12:13], v[14:15]
	s_nop 0
	v_add_f32_e32 v14, v14, v16
	v_add_f32_e32 v22, v15, v14
	v_and_b32_e32 v15, 0xffff0000, v31
	v_and_b32_e32 v14, 0xffff0000, v30
	v_lshlrev_b32_e32 v16, 16, v30
	v_pk_mul_f32 v[0:1], v[14:15], v[14:15]
	s_nop 0
	v_pk_fma_f32 v[0:1], v[16:17], v[16:17], v[0:1]
	s_nop 0
	v_add_f32_e32 v0, v0, v22
	v_and_b32_e32 v22, 0xffff0000, v32
	global_load_dwordx4 v[30:33], v[98:99], off
	v_add_f32_e32 v26, v1, v0
	v_pk_mul_f32 v[0:1], v[22:23], v[22:23]
	s_nop 0
	v_pk_fma_f32 v[0:1], v[24:25], v[24:25], v[0:1]
	s_nop 0
	v_add_f32_e32 v0, v0, v26
	v_add_f32_e32 v0, v1, v0
	ds_bpermute_b32 v1, v152, v0
	s_waitcnt lgkmcnt(0)
	v_add_f32_e32 v0, v0, v1
	ds_bpermute_b32 v1, v153, v0
	s_waitcnt lgkmcnt(0)
	v_add_f32_e32 v0, v0, v1
	v_fmamk_f32 v0, v0, 0x3c000000, v164
	v_cmp_gt_f32_e32 vcc, s33, v0
	v_mul_f32_e32 v1, 0x4b800000, v0
	s_nop 0
	v_cndmask_b32_e32 v0, v0, v1, vcc
	v_rsq_f32_e32 v0, v0
	s_nop 0
	v_mul_f32_e32 v1, 0x45800000, v0
	v_cndmask_b32_e32 v0, v0, v1, vcc
	v_mul_f32_e32 v26, 0x3e0293ee, v0
	v_mul_f32_e32 v0, v26, v29
	v_mul_f32_e32 v1, v26, v38
	v_mul_f32_e32 v29, v26, v40
	v_mul_f32_e32 v2, v26, v2
	v_mul_f32_e32 v4, v26, v4
	v_mul_f32_e32 v3, v26, v3
	v_mul_f32_e32 v27, v26, v27
	v_mul_f32_e32 v5, v26, v5
	v_mul_f32_e32 v21, v26, v21
	v_mul_f32_e32 v6, v26, v6
	v_mul_f32_e32 v20, v26, v20
	v_mul_f32_e32 v7, v26, v7
	v_mul_f32_e32 v18, v26, v18
	v_mul_f32_e32 v8, v26, v8
	v_mul_f32_e32 v9, v26, v9
	v_mul_f32_e32 v12, v26, v12
	v_mul_f32_e32 v10, v26, v10
	v_mul_f32_e32 v11, v26, v11
	v_mov_b32_e32 v38, v119
	v_mov_b32_e32 v40, v119
	s_waitcnt vmcnt(0)
	v_mul_f32_e32 v0, v30, v0
	v_mul_f32_e32 v1, v31, v1
	v_mul_f32_e32 v0, v34, v0
	v_mul_f32_e32 v1, v35, v1
	v_cvt_pk_bf16_f32 v0, v0, v1
	v_mul_f32_e32 v1, v26, v39
	v_mul_f32_e32 v1, v32, v1
	v_mul_f32_e32 v29, v33, v29
	global_load_dwordx4 v[30:33], v[98:99], off offset:16
	v_mul_f32_e32 v1, v36, v1
	v_mul_f32_e32 v29, v37, v29
	global_load_dwordx4 v[34:37], v[100:101], off offset:16
	v_cvt_pk_bf16_f32 v1, v1, v29
	v_mul_f32_e32 v29, v26, v41
	v_mov_b32_e32 v39, v119
	v_mov_b32_e32 v41, v119
	s_waitcnt vmcnt(1)
	v_mul_f32_e32 v29, v30, v29
	v_mul_f32_e32 v2, v31, v2
	v_mul_f32_e32 v4, v32, v4
	v_mul_f32_e32 v3, v33, v3
	global_load_dwordx4 v[30:33], v[98:99], off offset:128
	s_waitcnt vmcnt(1)
	v_mul_f32_e32 v29, v34, v29
	v_mul_f32_e32 v2, v35, v2
	v_mul_f32_e32 v4, v36, v4
	v_mul_f32_e32 v3, v37, v3
	global_load_dwordx4 v[34:37], v[100:101], off offset:128
	v_cvt_pk_bf16_f32 v3, v4, v3
	v_mul_f32_e32 v4, v26, v42
	v_cvt_pk_bf16_f32 v2, v29, v2
	v_mov_b32_e32 v42, v119
	s_waitcnt vmcnt(1)
; __device__ __forceinline__ unsigned cvt_pk_bf16(float lo, float hi) { unsigned r; asm("v_cvt_pk_bf16_f32 %0, %1, %2" : "=v"(r) : "v"(lo), "v"(hi)); return r; }
; __device__ __forceinline__ float lo_bf(unsigned u) { return __uint_as_float(u << 16); }
; __device__ __forceinline__ float hi_bf(unsigned u) { return __uint_as_float(u & 0xffff0000u); }
; __device__ __forceinline__ void attn_phase(const Params& p, int l, bf16_t* PROJ, LAS unsigned char* L) {
;     ...
;             for (int ks = 0; ks < 4; ++ks) { const float* gp = gq + ks * 32 + fq * 8; const float* gkp = gk + ks * 32 + fq * 8; u32x4 w;
; #pragma unroll
;                 for (int e = 0; e < 4; ++e) w[e] = cvt_pk_bf16(lo_bf(raw[ks][e]) * rs * gp[2 * e] * gkp[2 * e], hi_bf(raw[ks][e]) * rs * gp[2 * e + 1] * gkp[2 * e + 1]);
;                 aq[ks] = __builtin_bit_cast(bf16x8, w); }
;         }
;         f32x4 O[8]; float mrow[4], lsum[4];
; #pragma unroll
;         for (int e = 0; e < 8; ++e) O[e] = (f32x4){0.f, 0.f, 0.f, 0.f};
; #pragma unroll
;         for (int j = 0; j < 4; ++j) { mrow[j] = -1e30f; lsum[j] = 0.f; }
;         const int jstart = n >= 8 ? 0 : 8 - n;
;         u32x4 kr[4]; u32x4 vr[2][2];
;     ...
;         ATT_LOAD(n - 8 + jstart);
	v_mul_f32_e32 v4, v30, v4
	v_mul_f32_e32 v27, v31, v27
	v_mul_f32_e32 v5, v5, v33
	s_waitcnt vmcnt(0)
	v_mul_f32_e32 v4, v34, v4
	v_mul_f32_e32 v27, v35, v27
	v_cvt_pk_bf16_f32 v4, v4, v27
	v_mul_f32_e32 v27, v26, v28
	global_load_dwordx4 v[28:31], v[98:99], off offset:144
	v_mul_f32_e32 v27, v32, v27
	global_load_dwordx4 v[32:35], v[100:101], off offset:144
	v_mul_f32_e32 v27, v36, v27
	v_mul_f32_e32 v5, v37, v5
	v_cvt_pk_bf16_f32 v5, v27, v5
	v_mov_b32_e32 v27, v119
	v_mov_b32_e32 v37, v119
	v_mov_b32_e32 v36, v119
	s_waitcnt vmcnt(1)
	v_mul_f32_e32 v21, v21, v28
	v_mul_f32_e32 v6, v6, v29
	v_mul_f32_e32 v20, v20, v30
	v_mul_f32_e32 v7, v7, v31
	global_load_dwordx4 v[28:31], v[98:99], off offset:256
	s_waitcnt vmcnt(1)
	v_mul_f32_e32 v21, v32, v21
	v_mul_f32_e32 v6, v33, v6
	v_mul_f32_e32 v20, v34, v20
	v_mul_f32_e32 v7, v35, v7
	global_load_dwordx4 v[32:35], v[100:101], off offset:256
	v_cvt_pk_bf16_f32 v6, v21, v6
	v_cvt_pk_bf16_f32 v7, v20, v7
	s_waitcnt vmcnt(1)
	v_mul_f32_e32 v18, v18, v28
	v_mul_f32_e32 v8, v8, v29
	v_mul_f32_e32 v9, v9, v31
	s_waitcnt vmcnt(0)
	v_mul_f32_e32 v18, v32, v18
	v_mul_f32_e32 v8, v33, v8
	v_cvt_pk_bf16_f32 v8, v18, v8
	v_mul_f32_e32 v18, v26, v19
	v_mul_f32_e32 v18, v18, v30
	v_mul_f32_e32 v18, v34, v18
	v_mul_f32_e32 v9, v35, v9
	v_cvt_pk_bf16_f32 v9, v18, v9
	global_load_dwordx4 v[18:21], v[98:99], off offset:272
	global_load_dwordx4 v[28:31], v[100:101], off offset:272
	v_mov_b32_e32 v35, v119
	v_mov_b32_e32 v34, v119
	v_mov_b32_e32 v33, v119
	v_mov_b32_e32 v32, v119
	s_waitcnt vmcnt(1)
	v_mul_f32_e32 v12, v12, v18
	v_mul_f32_e32 v10, v10, v19
	s_waitcnt vmcnt(0)
	v_mul_f32_e32 v12, v28, v12
	v_mul_f32_e32 v10, v29, v10
	v_cvt_pk_bf16_f32 v10, v12, v10
	v_mul_f32_e32 v12, v26, v13
	v_mul_f32_e32 v12, v12, v20
	v_mul_f32_e32 v11, v11, v21
	global_load_dwordx4 v[18:21], v[98:99], off offset:384
	v_mul_f32_e32 v12, v30, v12
	v_mul_f32_e32 v11, v31, v11
	global_load_dwordx4 v[28:31], v[100:101], off offset:384
	v_cvt_pk_bf16_f32 v11, v12, v11
	v_mul_f32_e32 v12, v26, v16
	v_mul_f32_e32 v13, v26, v14
	v_mul_f32_e32 v14, v26, v15
	s_waitcnt vmcnt(1)
	v_mul_f32_e32 v12, v12, v18
	v_mul_f32_e32 v13, v13, v19
	v_mul_f32_e32 v14, v14, v21
	s_waitcnt vmcnt(0)
	v_mul_f32_e32 v12, v28, v12
	v_mul_f32_e32 v13, v29, v13
	v_cvt_pk_bf16_f32 v12, v12, v13
	v_mul_f32_e32 v13, v26, v17
	v_mul_f32_e32 v13, v13, v20
	v_mul_f32_e32 v13, v30, v13
	v_mul_f32_e32 v14, v31, v14
	v_cvt_pk_bf16_f32 v13, v13, v14
	global_load_dwordx4 v[14:17], v[98:99], off offset:400
	v_mul_f32_e32 v18, v26, v24
	v_mov_b32_e32 v24, v119
	v_mov_b32_e32 v31, v119
	v_mov_b32_e32 v30, v119
	v_mov_b32_e32 v29, v119
	v_mov_b32_e32 v28, v119
	s_waitcnt vmcnt(0)
	v_mul_f32_e32 v14, v18, v14
	global_load_dwordx4 v[18:21], v[100:101], off offset:400
	s_waitcnt vmcnt(0)
	v_mul_f32_e32 v14, v18, v14
	v_mul_f32_e32 v18, v26, v22
	v_mul_f32_e32 v15, v18, v15
	v_mul_f32_e32 v15, v19, v15
	v_cvt_pk_bf16_f32 v14, v14, v15
	v_mul_f32_e32 v15, v26, v25
	v_mul_f32_e32 v15, v15, v16
	v_mul_f32_e32 v16, v26, v23
	v_mul_f32_e32 v16, v16, v17
	v_mul_f32_e32 v15, v20, v15
	v_mul_f32_e32 v16, v21, v16
	v_cvt_pk_bf16_f32 v15, v15, v16
	v_mov_b32_e32 v19, v119
	v_mov_b32_e32 v18, v119
	v_mov_b32_e32 v17, v119
	v_mov_b32_e32 v16, v119
	v_mov_b32_e32 v23, v119
	v_mov_b32_e32 v22, v119
	v_mov_b32_e32 v21, v119
	v_mov_b32_e32 v20, v119
	v_mov_b32_e32 v26, v119
	v_mov_b32_e32 v25, v119
	s_cbranch_scc0 .LBB0_335
	s_add_i32 s20, s3, s20
	s_lshl_b32 s40, s20, 6
	s_lshl_b32 s34, s36, 7
	s_add_i32 s41, s40, 0xfffffe00
	s_or_b32 s35, s34, 0x80
	s_mul_i32 s21, s41, 0x5000
	s_mul_hi_i32 s20, s41, 0x5000
	s_add_u32 s21, s14, s21
	s_addc_u32 s22, s15, s20
	s_add_u32 s20, s21, 0x1000
	s_addc_u32 s21, s22, 0
	s_lshl_b32 s22, s36, 8
	s_add_u32 s22, s20, s22
	s_addc_u32 s23, s21, 0
	v_lshlrev_b32_e32 v136, 1, v102
	v_lshl_add_u64 v[20:21], s[22:23], 0, v[136:137]
	v_lshl_add_u64 v[22:23], v[20:21], 0, v[104:105]
	v_lshl_add_u64 v[20:21], v[20:21], 0, v[106:107]
	global_load_dwordx4 v[48:51], v[22:23], off
	global_load_dwordx4 v[52:55], v[20:21], off
	v_lshl_add_u64 v[20:21], s[20:21], 0, v[136:137]
	v_add_lshl_u32 v120, s36, v161, 7
	v_add_lshl_u32 v16, s36, v182, 7
	v_add_lshl_u32 v122, s36, v184, 7
	v_add_lshl_u32 v18, s36, v185, 7
	v_lshl_add_u64 v[22:23], v[20:21], 0, v[104:105]
	s_lshl_b32 s36, s35, 1
	v_lshl_add_u64 v[20:21], v[20:21], 0, v[106:107]
	v_lshl_add_u64 v[22:23], v[22:23], 0, s[36:37]
	v_lshl_add_u64 v[20:21], v[20:21], 0, s[36:37]
	v_ashrrev_i32_e32 v19, 31, v18
	global_load_dwordx4 v[72:75], v[22:23], off
	global_load_dwordx4 v[76:79], v[20:21], off
	v_or_b32_e32 v22, s41, v186
	v_mov_b64_e32 v[20:21], s[14:15]
	v_mad_i64_i32 v[22:23], s[20:21], v22, s62, v[20:21]
	v_lshlrev_b64 v[18:19], 1, v[18:19]
	v_or_b32_e32 v24, s41, v181
	v_ashrrev_i32_e32 v123, 31, v122
	v_lshl_add_u64 v[22:23], v[22:23], 0, v[18:19]
	v_mad_i64_i32 v[24:25], s[20:21], v24, s62, v[20:21]
	v_lshl_add_u64 v[22:23], v[22:23], 0, v[136:137]
	v_lshl_add_u64 v[26:27], v[122:123], 1, v[24:25]
	v_ashrrev_i32_e32 v17, 31, v16
	v_lshl_add_u64 v[26:27], v[26:27], 0, v[136:137]
	global_load_dwordx4 v[56:59], v[22:23], off offset:2048
	global_load_dwordx4 v[60:63], v[26:27], off offset:2048
	v_or_b32_e32 v22, s41, v183
	v_mad_i64_i32 v[20:21], s[20:21], v22, s62, v[20:21]
	v_lshlrev_b64 v[16:17], 1, v[16:17]
	v_ashrrev_i32_e32 v121, 31, v120
	v_lshl_add_u64 v[20:21], v[20:21], 0, v[16:17]
	v_lshl_add_u64 v[20:21], v[20:21], 0, v[136:137]
	v_lshl_add_u64 v[22:23], v[120:121], 1, v[24:25]
	v_lshl_add_u64 v[22:23], v[22:23], 0, v[136:137]
	global_load_dwordx4 v[64:67], v[20:21], off offset:2048
	global_load_dwordx4 v[68:71], v[22:23], off offset:2048
	s_lshl_b32 s20, s3, 6
	v_mov_b32_e32 v44, 0
	v_lshl_add_u64 v[124:125], v[110:111], 0, v[16:17]
	v_lshl_add_u64 v[126:127], v[110:111], 0, v[18:19]
	v_subrev_u32_e32 v113, s20, v195
	s_add_i32 s22, s40, 0xfffffe40
	v_mov_b32_e32 v217, 0xf149f2ca
	s_lshl_b32 s23, s34, 1
	s_lshl_b32 s36, s35, 1
	v_mov_b32_e32 v218, 0xf149f2ca
	v_mov_b32_e32 v219, 0xf149f2ca
	v_mov_b32_e32 v220, 0xf149f2ca
	v_mov_b32_e32 v45, v44
	v_mov_b32_e32 v46, v44
	v_mov_b32_e32 v47, v44
	v_mov_b32_e32 v40, v44
	v_mov_b32_e32 v41, v44
	v_mov_b32_e32 v42, v44
	v_mov_b32_e32 v43, v44
	v_mov_b32_e32 v36, v44
	v_mov_b32_e32 v37, v44
	v_mov_b32_e32 v38, v44
	v_mov_b32_e32 v39, v44
	v_mov_b32_e32 v32, v44
	v_mov_b32_e32 v33, v44
	v_mov_b32_e32 v34, v44
	v_mov_b32_e32 v35, v44
	v_mov_b32_e32 v28, v44
	v_mov_b32_e32 v29, v44
	v_mov_b32_e32 v30, v44
	v_mov_b32_e32 v31, v44
	v_mov_b32_e32 v24, v44
	v_mov_b32_e32 v25, v44
	v_mov_b32_e32 v26, v44
	v_mov_b32_e32 v27, v44
	v_mov_b32_e32 v20, v44
	v_mov_b32_e32 v21, v44
	v_mov_b32_e32 v22, v44
	v_mov_b32_e32 v23, v44
	v_mov_b32_e32 v16, v44
	v_mov_b32_e32 v17, v44
	v_mov_b32_e32 v18, v44
	v_mov_b32_e32 v19, v44
	v_mov_b32_e32 v116, v44
	v_mov_b32_e32 v117, v44
	v_mov_b32_e32 v118, v44
	v_mov_b32_e32 v119, v44
